# attention group-A loop: this step's K fragment LDS reads issued ahead of the DMA issue block (their latency passes under it)
# baseline (speedup 1.0000x reference)
.LBB0_232:
	s_add_i32 s3, s65, 0xffff0000
	s_and_b32 s3, s3, 0x18000
	v_add_u32_e32 v80, s3, v171
	ds_read_b128 v[96:99], v80
	ds_read_b128 v[116:119], v80 offset:512
	ds_read_b128 v[120:123], v80 offset:2048
	ds_read_b128 v[124:127], v80 offset:2560
	ds_read_b128 v[146:149], v80 offset:4096
	ds_read_b128 v[150:153], v80 offset:4608
	ds_read_b128 v[154:157], v80 offset:6144
	ds_read_b128 v[158:161], v80 offset:6656
	s_cmp_lt_u32 s16, 2
	s_cselect_b64 s[62:63], -1, 0
	s_cmp_ge_u32 s16, s67
	s_cselect_b64 s[76:77], -1, 0
	s_or_b64 s[62:63], s[62:63], s[76:77]
	s_and_b64 vcc, exec, s[62:63]
	s_cbranch_vccnz .LBB0_234
	s_and_b32 s3, s65, 0x18000
	s_add_i32 s3, s3, 0
	s_add_u32 s8, s27, s40
	s_addc_u32 s88, s50, s41
	s_add_u32 s76, s8, 0xe2c0400
	s_addc_u32 s77, s88, 0
	s_add_i32 s89, s37, s3
	s_mov_b32 s94, m0
	s_mov_b32 m0, s89
	s_nop 0
	global_load_lds_dwordx4 v167, s[76:77]
	s_mov_b32 m0, s94
	s_add_u32 s76, s8, 0xe2c0480
	s_addc_u32 s77, s88, 0
	s_addk_i32 s89, 0x2000
	s_addk_i32 s3, 0x4000
	s_mov_b32 s8, m0
	s_mov_b32 m0, s89
	s_nop 0
	global_load_lds_dwordx4 v167, s[76:77]
	s_mov_b32 m0, s8
	s_add_u32 s76, s9, s40
	s_addc_u32 s77, s30, s41
	s_add_i32 s8, s3, s54
	s_mov_b32 s88, m0
	s_mov_b32 m0, s8
	s_nop 0
	global_load_lds_dwordx4 v168, s[76:77]
	s_mov_b32 m0, s88
	s_add_u32 s76, s14, s40
	s_addc_u32 s77, s17, s41
	s_add_i32 s3, s3, s55
	s_mov_b32 s8, m0
	s_mov_b32 m0, s3
	s_nop 0
	global_load_lds_dwordx4 v168, s[76:77]
	s_mov_b32 m0, s8
.LBB0_234:
	s_add_i32 s3, s65, 0xffff0000
	s_and_b32 s3, s3, 0x18000
	s_setprio 1
	s_waitcnt lgkmcnt(7)
	v_mfma_f32_32x32x16_bf16 v[80:95], v[96:99], v[142:145], v[16:31]
	v_mov_b64_e32 v[110:111], v[30:31]
	v_mov_b64_e32 v[108:109], v[28:29]
	v_mov_b64_e32 v[106:107], v[26:27]
	v_mov_b64_e32 v[104:105], v[24:25]
	v_mov_b64_e32 v[102:103], v[22:23]
	v_mov_b64_e32 v[100:101], v[20:21]
	v_mov_b64_e32 v[98:99], v[18:19]
	v_mov_b64_e32 v[96:97], v[16:17]
	s_waitcnt lgkmcnt(5)
	v_mfma_f32_32x32x16_bf16 v[80:95], v[120:123], v[138:141], v[80:95]
	v_mfma_f32_32x32x16_bf16 v[96:111], v[116:119], v[142:145], v[96:111]
	s_waitcnt lgkmcnt(4)
	v_mfma_f32_32x32x16_bf16 v[96:111], v[124:127], v[138:141], v[96:111]
	s_waitcnt lgkmcnt(3)
	v_mfma_f32_32x32x16_bf16 v[80:95], v[146:149], v[134:137], v[80:95]
	s_waitcnt lgkmcnt(2)
	v_mfma_f32_32x32x16_bf16 v[96:111], v[150:153], v[134:137], v[96:111]
	s_waitcnt lgkmcnt(1)
	v_mfma_f32_32x32x16_bf16 v[80:95], v[154:157], v[130:133], v[80:95]
	s_waitcnt lgkmcnt(0)
	v_mfma_f32_32x32x16_bf16 v[96:111], v[158:161], v[130:133], v[96:111]
	s_setprio 0
	s_nop 15
	s_nop 7
	s_nop 0
	v_max3_f32 v116, v80, v81, v96
	v_max3_f32 v117, v82, v83, v97
	s_nop 0
	v_max3_f32 v116, v116, v98, v99
	v_max3_f32 v117, v117, v86, v87
	s_nop 0
	v_max3_f32 v116, v116, v84, v85
	v_max3_f32 v117, v117, v102, v103
	s_nop 0
	v_max3_f32 v116, v116, v100, v101
	v_max3_f32 v117, v117, v90, v91
	s_nop 0
	v_max3_f32 v116, v116, v88, v89
	v_max3_f32 v117, v117, v106, v107
	s_nop 0
	v_max3_f32 v116, v116, v104, v105
	v_max3_f32 v117, v117, v94, v95
	s_nop 0
	v_max3_f32 v116, v116, v92, v93
	v_max3_f32 v117, v117, v110, v111
	s_nop 0
	v_max3_f32 v116, v116, v108, v109
	s_nop 0
	v_max_f32_e32 v116, v116, v117
	s_nop 0
	v_mov_b32_e32 v117, v116
	s_nop 1
	v_permlane32_swap_b32_e32 v116, v117
	v_max_f32_e32 v116, v116, v117
	s_nop 0
	v_cmp_lt_f32_e32 vcc, s4, v116
	s_cbranch_vccz .LBB0_238
	v_max_f32_e32 v16, v116, v116
	v_max_f32_e32 v16, 0, v16
	v_exp_f32_e64 v17, -v16
	s_and_saveexec_b64 s[76:77], s[38:39]
	ds_write_b32 v113, v17
	s_or_b64 exec, exec, s[76:77]
	s_waitcnt lgkmcnt(0)
	ds_read_b128 v[18:21], v115
	ds_read_b128 v[22:25], v115 offset:32
	ds_read_b128 v[26:29], v115 offset:64
	ds_read_b128 v[116:119], v115 offset:96
	v_add_f32_e32 v114, v114, v16
	v_xor_b32_e32 v31, 0x80000000, v114
	v_pk_add_f32 v[80:81], v[80:81], v[16:17] op_sel_hi:[1,0] neg_lo:[0,1] neg_hi:[0,1]
	v_pk_add_f32 v[96:97], v[96:97], v[16:17] op_sel_hi:[1,0] neg_lo:[0,1] neg_hi:[0,1]
	v_pk_add_f32 v[82:83], v[82:83], v[16:17] op_sel_hi:[1,0] neg_lo:[0,1] neg_hi:[0,1]
	v_pk_add_f32 v[98:99], v[98:99], v[16:17] op_sel_hi:[1,0] neg_lo:[0,1] neg_hi:[0,1]
	v_pk_add_f32 v[84:85], v[84:85], v[16:17] op_sel_hi:[1,0] neg_lo:[0,1] neg_hi:[0,1]
	v_pk_add_f32 v[100:101], v[100:101], v[16:17] op_sel_hi:[1,0] neg_lo:[0,1] neg_hi:[0,1]
	v_pk_add_f32 v[86:87], v[86:87], v[16:17] op_sel_hi:[1,0] neg_lo:[0,1] neg_hi:[0,1]
	v_pk_add_f32 v[102:103], v[102:103], v[16:17] op_sel_hi:[1,0] neg_lo:[0,1] neg_hi:[0,1]
	v_pk_add_f32 v[88:89], v[88:89], v[16:17] op_sel_hi:[1,0] neg_lo:[0,1] neg_hi:[0,1]
	v_pk_add_f32 v[104:105], v[104:105], v[16:17] op_sel_hi:[1,0] neg_lo:[0,1] neg_hi:[0,1]
	v_pk_add_f32 v[90:91], v[90:91], v[16:17] op_sel_hi:[1,0] neg_lo:[0,1] neg_hi:[0,1]
	v_pk_add_f32 v[106:107], v[106:107], v[16:17] op_sel_hi:[1,0] neg_lo:[0,1] neg_hi:[0,1]
	v_pk_add_f32 v[92:93], v[92:93], v[16:17] op_sel_hi:[1,0] neg_lo:[0,1] neg_hi:[0,1]
	v_pk_add_f32 v[108:109], v[108:109], v[16:17] op_sel_hi:[1,0] neg_lo:[0,1] neg_hi:[0,1]
	v_pk_add_f32 v[94:95], v[94:95], v[16:17] op_sel_hi:[1,0] neg_lo:[0,1] neg_hi:[0,1]
	v_pk_add_f32 v[110:111], v[110:111], v[16:17] op_sel_hi:[1,0] neg_lo:[0,1] neg_hi:[0,1]
	s_waitcnt lgkmcnt(0)
	v_pk_mul_f32 v[44:45], v[44:45], v[116:117]
	v_pk_mul_f32 v[40:41], v[40:41], v[26:27]
	v_pk_mul_f32 v[36:37], v[36:37], v[22:23]
	v_pk_mul_f32 v[46:47], v[46:47], v[118:119]
	v_pk_mul_f32 v[42:43], v[42:43], v[28:29]
	v_pk_mul_f32 v[38:39], v[38:39], v[24:25]
	v_pk_mul_f32 v[34:35], v[34:35], v[20:21]
	v_pk_mul_f32 v[32:33], v[32:33], v[18:19]
	v_pk_mul_f32 v[60:61], v[60:61], v[116:117]
	v_pk_mul_f32 v[56:57], v[56:57], v[26:27]
	v_pk_mul_f32 v[52:53], v[52:53], v[22:23]
	v_pk_mul_f32 v[62:63], v[62:63], v[118:119]
	v_pk_mul_f32 v[58:59], v[58:59], v[28:29]
	v_pk_mul_f32 v[54:55], v[54:55], v[24:25]
	v_pk_mul_f32 v[50:51], v[50:51], v[20:21]
	v_pk_mul_f32 v[48:49], v[48:49], v[18:19]
	v_pk_mul_f32 v[76:77], v[76:77], v[116:117]
	v_pk_mul_f32 v[72:73], v[72:73], v[26:27]
	v_pk_mul_f32 v[68:69], v[68:69], v[22:23]
	v_pk_mul_f32 v[78:79], v[78:79], v[118:119]
	v_pk_mul_f32 v[74:75], v[74:75], v[28:29]
	v_pk_mul_f32 v[70:71], v[70:71], v[24:25]
	v_pk_mul_f32 v[66:67], v[66:67], v[20:21]
	v_pk_mul_f32 v[64:65], v[64:65], v[18:19]
	v_pk_mul_f32 v[12:13], v[12:13], v[116:117]
	v_pk_mul_f32 v[8:9], v[8:9], v[26:27]
	v_pk_mul_f32 v[4:5], v[4:5], v[22:23]
	v_pk_mul_f32 v[14:15], v[14:15], v[118:119]
	v_pk_mul_f32 v[10:11], v[10:11], v[28:29]
	v_pk_mul_f32 v[6:7], v[6:7], v[24:25]
	v_pk_mul_f32 v[2:3], v[2:3], v[20:21]
	v_pk_mul_f32 v[0:1], v[0:1], v[18:19]
	v_mul_f32_e32 v112, v112, v17
	v_mov_b32_e32 v30, v31
	v_mov_b32_e32 v29, v31
	v_mov_b32_e32 v28, v31
	v_mov_b32_e32 v27, v31
	v_mov_b32_e32 v26, v31
	v_mov_b32_e32 v25, v31
	v_mov_b32_e32 v24, v31
	v_mov_b32_e32 v23, v31
	v_mov_b32_e32 v22, v31
	v_mov_b32_e32 v21, v31
	v_mov_b32_e32 v20, v31
	v_mov_b32_e32 v19, v31
	v_mov_b32_e32 v18, v31
	v_mov_b32_e32 v17, v31
	v_mov_b32_e32 v16, v31
